# same as previous but without the early barrier L1 invalidate (A/B of that edit)
# baseline (speedup 1.0000x reference)
; __device__ __forceinline__ unsigned xb_ld(unsigned* p)              { return __hip_atomic_load(p, __ATOMIC_RELAXED, __HIP_MEMORY_SCOPE_AGENT); }
; __device__ __forceinline__ unsigned xb_add(unsigned* p, unsigned v) { return __hip_atomic_fetch_add(p, v, __ATOMIC_RELAXED, __HIP_MEMORY_SCOPE_AGENT); }
; #define XB_SPIN(cond, bar) do { unsigned _sp = 0; while (cond) { __builtin_amdgcn_s_sleep(1); \
;     if ((++_sp & 255u) == 0u) { if (xb_ld(&(bar)[XB_TMO])) break; if (_sp > XB_SPIN_CAP) { atomicAdd(&(bar)[XB_TMO], 1u); break; } } } } while (0)
; __device__ __forceinline__ void xcd_barrier(const XcdBarrier& b) {
;     ...
;         __builtin_amdgcn_s_waitcnt(0);
;         unsigned nloc = b.st[0], nx = b.st[1];
;         if (nloc == 0u) { xcd_barrier_complete(bar, b.x, nloc, nx); b.st[0] = nloc; b.st[1] = nx; }
;         const unsigned old = xb_add(&bar[XB_XSUB(b.x)], 1u);
;         const unsigned gen = old / nloc;
;         if (old + 1u == (gen + 1u) * nloc) {
;             __builtin_amdgcn_fence(__ATOMIC_RELEASE, "agent");
;             asm volatile("s_waitcnt vmcnt(0)" ::: "memory");
;             const unsigned og = xb_add(&bar[XB_TOP], 1u);
;             const unsigned tg = og / nx;
;             if (og + 1u == (tg + 1u) * nx) xb_add(&bar[XB_TOPGEN], 1u);
;             else XB_SPIN(xb_ld(&bar[XB_TOPGEN]) == tg, bar);
;             __builtin_amdgcn_fence(__ATOMIC_ACQUIRE, "agent");
;             xb_add(&bar[XB_XGEN(b.x)], 1u);
;             asm volatile("s_waitcnt vmcnt(0)" ::: "memory");
;         } else {
;             XB_SPIN(xb_ld(&bar[XB_XGEN(b.x)]) == gen, bar);
.LBB0_84:
	s_or_b64 exec, exec, s[2:3]
	v_cvt_f32_u32_e32 v4, v2
	s_waitcnt vmcnt(0)
	v_readfirstlane_b32 s2, v3
	v_sub_u32_e32 v3, 0, v2
	v_rcp_iflag_f32_e32 v4, v4
	v_add_u32_e32 v5, s2, v1
	v_mul_f32_e32 v4, 0x4f7ffffe, v4
	v_cvt_u32_f32_e32 v4, v4
	v_mul_lo_u32 v1, v3, v4
	v_mul_hi_u32 v1, v4, v1
	v_add_u32_e32 v1, v4, v1
	v_mul_hi_u32 v1, v5, v1
	v_mul_lo_u32 v3, v1, v2
	v_sub_u32_e32 v3, v5, v3
	v_add_u32_e32 v4, 1, v1
	v_sub_u32_e32 v6, v3, v2
	v_cmp_ge_u32_e32 vcc, v3, v2
	s_nop 1
	v_cndmask_b32_e32 v1, v1, v4, vcc
	v_cndmask_b32_e32 v3, v3, v6, vcc
	v_add_u32_e32 v4, 1, v1
	v_cmp_ge_u32_e32 vcc, v3, v2
	v_add_u32_e32 v3, 1, v5
	s_nop 0
	v_cndmask_b32_e32 v1, v1, v4, vcc
	v_mul_lo_u32 v4, v2, v1
	v_add_u32_e32 v2, v4, v2
	v_cmp_ne_u32_e32 vcc, v3, v2
	s_and_saveexec_b64 s[2:3], vcc
	s_xor_b64 s[2:3], exec, s[2:3]
	s_cbranch_execz .LBB0_98
	v_readlane_b32 s4, v252, 3
	v_readlane_b32 s5, v252, 4
	s_waitcnt lgkmcnt(0)
	s_nop 3
	global_load_dword v0, v197, s[4:5] sc1
	s_waitcnt vmcnt(0)
	v_cmp_eq_u32_e32 vcc, v0, v1
	s_and_saveexec_b64 s[4:5], vcc
	s_cbranch_execz .LBB0_97
	s_mov_b32 s22, 1
	s_mov_b64 s[6:7], 0
	s_branch .LBB0_88

; __device__ __forceinline__ unsigned xb_ld(unsigned* p)              { return __hip_atomic_load(p, __ATOMIC_RELAXED, __HIP_MEMORY_SCOPE_AGENT); }
; __device__ __forceinline__ unsigned xb_add(unsigned* p, unsigned v) { return __hip_atomic_fetch_add(p, v, __ATOMIC_RELAXED, __HIP_MEMORY_SCOPE_AGENT); }
; #define XB_SPIN(cond, bar) do { unsigned _sp = 0; while (cond) { __builtin_amdgcn_s_sleep(1); \
;     if ((++_sp & 255u) == 0u) { if (xb_ld(&(bar)[XB_TMO])) break; if (_sp > XB_SPIN_CAP) { atomicAdd(&(bar)[XB_TMO], 1u); break; } } } } while (0)
; __device__ __forceinline__ void xcd_barrier(const XcdBarrier& b) {
;     ...
;         const unsigned old = xb_add(&bar[XB_XSUB(b.x)], 1u);
;         const unsigned gen = old / nloc;
;         if (old + 1u == (gen + 1u) * nloc) {
;             __builtin_amdgcn_fence(__ATOMIC_RELEASE, "agent");
;             asm volatile("s_waitcnt vmcnt(0)" ::: "memory");
;             const unsigned og = xb_add(&bar[XB_TOP], 1u);
;             const unsigned tg = og / nx;
;             if (og + 1u == (tg + 1u) * nx) xb_add(&bar[XB_TOPGEN], 1u);
;             else XB_SPIN(xb_ld(&bar[XB_TOPGEN]) == tg, bar);
;             __builtin_amdgcn_fence(__ATOMIC_ACQUIRE, "agent");
;             xb_add(&bar[XB_XGEN(b.x)], 1u);
;             asm volatile("s_waitcnt vmcnt(0)" ::: "memory");
;         } else {
;             XB_SPIN(xb_ld(&bar[XB_XGEN(b.x)]) == gen, bar);
;             __builtin_amdgcn_fence(__ATOMIC_ACQUIRE, "agent");
;             asm volatile("s_waitcnt vmcnt(0)" ::: "memory");
.LBB0_97:
	s_or_b64 exec, exec, s[4:5]
	s_waitcnt vmcnt(0)
	buffer_inv sc1
	s_waitcnt vmcnt(0)
.LBB0_98:
	s_andn2_saveexec_b64 s[2:3], s[2:3]
	s_cbranch_execz .LBB0_118
	s_mov_b64 s[4:5], exec
	buffer_wbl2 sc1
	s_waitcnt lgkmcnt(0)
	s_waitcnt vmcnt(0)
	v_mbcnt_lo_u32_b32 v1, s4, 0
	v_mbcnt_hi_u32_b32 v1, s5, v1
	v_cmp_eq_u32_e32 vcc, 0, v1
	s_and_saveexec_b64 s[6:7], vcc
	s_cbranch_execz .LBB0_101
	s_bcnt1_i32_b64 s4, s[4:5]
	v_mov_b32_e32 v2, s4
	v_readlane_b32 s4, v252, 5
	v_readlane_b32 s5, v252, 6
	s_nop 4
	global_atomic_add v2, v197, v2, s[4:5] sc0

; __device__ __forceinline__ unsigned xb_ld(unsigned* p)              { return __hip_atomic_load(p, __ATOMIC_RELAXED, __HIP_MEMORY_SCOPE_AGENT); }
; __device__ __forceinline__ unsigned xb_add(unsigned* p, unsigned v) { return __hip_atomic_fetch_add(p, v, __ATOMIC_RELAXED, __HIP_MEMORY_SCOPE_AGENT); }
; #define XB_SPIN(cond, bar) do { unsigned _sp = 0; while (cond) { __builtin_amdgcn_s_sleep(1); \
;     if ((++_sp & 255u) == 0u) { if (xb_ld(&(bar)[XB_TMO])) break; if (_sp > XB_SPIN_CAP) { atomicAdd(&(bar)[XB_TMO], 1u); break; } } } } while (0)
; __device__ __forceinline__ void xcd_barrier(const XcdBarrier& b) {
;     ...
;             const unsigned og = xb_add(&bar[XB_TOP], 1u);
;             const unsigned tg = og / nx;
;             if (og + 1u == (tg + 1u) * nx) xb_add(&bar[XB_TOPGEN], 1u);
;             else XB_SPIN(xb_ld(&bar[XB_TOPGEN]) == tg, bar);
;             __builtin_amdgcn_fence(__ATOMIC_ACQUIRE, "agent");
;             xb_add(&bar[XB_XGEN(b.x)], 1u);
;             asm volatile("s_waitcnt vmcnt(0)" ::: "memory");
.LBB0_115:
	s_or_b64 exec, exec, s[4:5]
	s_mov_b64 s[4:5], exec
	v_mbcnt_lo_u32_b32 v0, s4, 0
	v_mbcnt_hi_u32_b32 v0, s5, v0
	v_cmp_eq_u32_e32 vcc, 0, v0
	s_waitcnt vmcnt(0)
	buffer_inv sc1
	s_and_saveexec_b64 s[6:7], vcc
	s_cbranch_execz .LBB0_117
	s_bcnt1_i32_b64 s4, s[4:5]
	v_mov_b32_e32 v0, s4
	v_readlane_b32 s4, v252, 3
	v_readlane_b32 s5, v252, 4
	s_nop 4
	global_atomic_add v197, v0, s[4:5]

; __device__ __forceinline__ unsigned xb_ld(unsigned* p)              { return __hip_atomic_load(p, __ATOMIC_RELAXED, __HIP_MEMORY_SCOPE_AGENT); }
; __device__ __forceinline__ unsigned xb_add(unsigned* p, unsigned v) { return __hip_atomic_fetch_add(p, v, __ATOMIC_RELAXED, __HIP_MEMORY_SCOPE_AGENT); }
; #define XB_SPIN(cond, bar) do { unsigned _sp = 0; while (cond) { __builtin_amdgcn_s_sleep(1); \
;     if ((++_sp & 255u) == 0u) { if (xb_ld(&(bar)[XB_TMO])) break; if (_sp > XB_SPIN_CAP) { atomicAdd(&(bar)[XB_TMO], 1u); break; } } } } while (0)
; __device__ __forceinline__ void xcd_barrier(const XcdBarrier& b) {
;     ...
;         __builtin_amdgcn_s_waitcnt(0);
;         unsigned nloc = b.st[0], nx = b.st[1];
;         if (nloc == 0u) { xcd_barrier_complete(bar, b.x, nloc, nx); b.st[0] = nloc; b.st[1] = nx; }
;         const unsigned old = xb_add(&bar[XB_XSUB(b.x)], 1u);
;         const unsigned gen = old / nloc;
;         if (old + 1u == (gen + 1u) * nloc) {
;             __builtin_amdgcn_fence(__ATOMIC_RELEASE, "agent");
;             asm volatile("s_waitcnt vmcnt(0)" ::: "memory");
;             const unsigned og = xb_add(&bar[XB_TOP], 1u);
;             const unsigned tg = og / nx;
;             if (og + 1u == (tg + 1u) * nx) xb_add(&bar[XB_TOPGEN], 1u);
;             else XB_SPIN(xb_ld(&bar[XB_TOPGEN]) == tg, bar);
;             __builtin_amdgcn_fence(__ATOMIC_ACQUIRE, "agent");
;             xb_add(&bar[XB_XGEN(b.x)], 1u);
;             asm volatile("s_waitcnt vmcnt(0)" ::: "memory");
;         } else {
;             XB_SPIN(xb_ld(&bar[XB_XGEN(b.x)]) == gen, bar);
.LBB0_328:
	s_or_b64 exec, exec, s[2:3]
	v_cvt_f32_u32_e32 v4, v2
	s_waitcnt vmcnt(0)
	v_readfirstlane_b32 s2, v3
	v_sub_u32_e32 v3, 0, v2
	v_rcp_iflag_f32_e32 v4, v4
	v_add_u32_e32 v5, s2, v1
	v_mul_f32_e32 v4, 0x4f7ffffe, v4
	v_cvt_u32_f32_e32 v4, v4
	v_mul_lo_u32 v1, v3, v4
	v_mul_hi_u32 v1, v4, v1
	v_add_u32_e32 v1, v4, v1
	v_mul_hi_u32 v1, v5, v1
	v_mul_lo_u32 v3, v1, v2
	v_sub_u32_e32 v3, v5, v3
	v_add_u32_e32 v4, 1, v1
	v_cmp_ge_u32_e32 vcc, v3, v2
	s_nop 1
	v_cndmask_b32_e32 v1, v1, v4, vcc
	v_sub_u32_e32 v4, v3, v2
	v_cndmask_b32_e32 v3, v3, v4, vcc
	v_add_u32_e32 v4, 1, v1
	v_cmp_ge_u32_e32 vcc, v3, v2
	v_add_u32_e32 v3, 1, v5
	s_nop 0
	v_cndmask_b32_e32 v1, v1, v4, vcc
	v_mul_lo_u32 v4, v2, v1
	v_add_u32_e32 v2, v4, v2
	v_cmp_ne_u32_e32 vcc, v3, v2
	s_and_saveexec_b64 s[2:3], vcc
	s_xor_b64 s[2:3], exec, s[2:3]
	s_cbranch_execz .LBB0_342
	v_readlane_b32 s4, v252, 3
	v_readlane_b32 s5, v252, 4
	s_waitcnt lgkmcnt(0)
	s_nop 3
	global_load_dword v0, v197, s[4:5] sc1
	s_waitcnt vmcnt(0)
	v_cmp_eq_u32_e32 vcc, v0, v1
	s_and_saveexec_b64 s[4:5], vcc
	s_cbranch_execz .LBB0_341
	s_mov_b32 s22, 1
	s_mov_b64 s[6:7], 0
	s_branch .LBB0_332

; __device__ __forceinline__ unsigned xb_add(unsigned* p, unsigned v) { return __hip_atomic_fetch_add(p, v, __ATOMIC_RELAXED, __HIP_MEMORY_SCOPE_AGENT); }
; __device__ __forceinline__ void xcd_barrier(const XcdBarrier& b) {
;     ...
;         if (old + 1u == (gen + 1u) * nloc) {
;             __builtin_amdgcn_fence(__ATOMIC_RELEASE, "agent");
;             asm volatile("s_waitcnt vmcnt(0)" ::: "memory");
;             const unsigned og = xb_add(&bar[XB_TOP], 1u);
.LBB0_540:
	s_andn2_saveexec_b64 s[2:3], s[2:3]
	s_cbranch_execz .LBB0_560
	s_mov_b64 s[2:3], exec
	buffer_wbl2 sc1
	s_waitcnt lgkmcnt(0)
	s_waitcnt vmcnt(0)
	v_mbcnt_lo_u32_b32 v1, s2, 0
	v_mbcnt_hi_u32_b32 v1, s3, v1
	v_cmp_eq_u32_e32 vcc, 0, v1
	s_and_saveexec_b64 s[4:5], vcc
	s_cbranch_execz .LBB0_543
	s_bcnt1_i32_b64 s2, s[2:3]
	v_mov_b32_e32 v2, s2
	v_readlane_b32 s2, v252, 5
	v_readlane_b32 s3, v252, 6
	s_nop 4
	global_atomic_add v2, v197, v2, s[2:3] sc0

; __device__ __forceinline__ unsigned xb_ld(unsigned* p)              { return __hip_atomic_load(p, __ATOMIC_RELAXED, __HIP_MEMORY_SCOPE_AGENT); }
; __device__ __forceinline__ unsigned xb_add(unsigned* p, unsigned v) { return __hip_atomic_fetch_add(p, v, __ATOMIC_RELAXED, __HIP_MEMORY_SCOPE_AGENT); }
; #define XB_SPIN(cond, bar) do { unsigned _sp = 0; while (cond) { __builtin_amdgcn_s_sleep(1); \
;     if ((++_sp & 255u) == 0u) { if (xb_ld(&(bar)[XB_TMO])) break; if (_sp > XB_SPIN_CAP) { atomicAdd(&(bar)[XB_TMO], 1u); break; } } } } while (0)
; __device__ __forceinline__ void xcd_barrier(const XcdBarrier& b) {
;     ...
;             if (og + 1u == (tg + 1u) * nx) xb_add(&bar[XB_TOPGEN], 1u);
;             else XB_SPIN(xb_ld(&bar[XB_TOPGEN]) == tg, bar);
;             __builtin_amdgcn_fence(__ATOMIC_ACQUIRE, "agent");
;             xb_add(&bar[XB_XGEN(b.x)], 1u);
;             asm volatile("s_waitcnt vmcnt(0)" ::: "memory");
.LBB0_557:
	s_or_b64 exec, exec, s[2:3]
	s_mov_b64 s[2:3], exec
	v_mbcnt_lo_u32_b32 v0, s2, 0
	v_mbcnt_hi_u32_b32 v0, s3, v0
	v_cmp_eq_u32_e32 vcc, 0, v0
	s_waitcnt vmcnt(0)
	buffer_inv sc1
	s_and_saveexec_b64 s[4:5], vcc
	s_cbranch_execz .LBB0_559
	s_bcnt1_i32_b64 s2, s[2:3]
	v_mov_b32_e32 v0, s2
	v_readlane_b32 s2, v252, 3
	v_readlane_b32 s3, v252, 4
	s_nop 4
	global_atomic_add v197, v0, s[2:3]

; __device__ __forceinline__ unsigned xb_ld(unsigned* p)              { return __hip_atomic_load(p, __ATOMIC_RELAXED, __HIP_MEMORY_SCOPE_AGENT); }
; __device__ __forceinline__ unsigned xb_add(unsigned* p, unsigned v) { return __hip_atomic_fetch_add(p, v, __ATOMIC_RELAXED, __HIP_MEMORY_SCOPE_AGENT); }
; #define XB_SPIN(cond, bar) do { unsigned _sp = 0; while (cond) { __builtin_amdgcn_s_sleep(1); \
;     if ((++_sp & 255u) == 0u) { if (xb_ld(&(bar)[XB_TMO])) break; if (_sp > XB_SPIN_CAP) { atomicAdd(&(bar)[XB_TMO], 1u); break; } } } } while (0)
; __device__ __forceinline__ void xcd_barrier(const XcdBarrier& b) {
;     ...
;         __builtin_amdgcn_s_waitcnt(0);
;         unsigned nloc = b.st[0], nx = b.st[1];
;         if (nloc == 0u) { xcd_barrier_complete(bar, b.x, nloc, nx); b.st[0] = nloc; b.st[1] = nx; }
;         const unsigned old = xb_add(&bar[XB_XSUB(b.x)], 1u);
;         const unsigned gen = old / nloc;
;         if (old + 1u == (gen + 1u) * nloc) {
;             __builtin_amdgcn_fence(__ATOMIC_RELEASE, "agent");
;             asm volatile("s_waitcnt vmcnt(0)" ::: "memory");
;             const unsigned og = xb_add(&bar[XB_TOP], 1u);
;             const unsigned tg = og / nx;
;             if (og + 1u == (tg + 1u) * nx) xb_add(&bar[XB_TOPGEN], 1u);
;             else XB_SPIN(xb_ld(&bar[XB_TOPGEN]) == tg, bar);
;             __builtin_amdgcn_fence(__ATOMIC_ACQUIRE, "agent");
;             xb_add(&bar[XB_XGEN(b.x)], 1u);
;             asm volatile("s_waitcnt vmcnt(0)" ::: "memory");
;         } else {
;             XB_SPIN(xb_ld(&bar[XB_XGEN(b.x)]) == gen, bar);
.LBB0_960:
	s_or_b64 exec, exec, s[6:7]
	v_cvt_f32_u32_e32 v4, v2
	s_waitcnt vmcnt(0)
	v_readfirstlane_b32 s3, v3
	v_sub_u32_e32 v3, 0, v2
	v_rcp_iflag_f32_e32 v4, v4
	v_add_u32_e32 v5, s3, v1
	v_mul_f32_e32 v4, 0x4f7ffffe, v4
	v_cvt_u32_f32_e32 v4, v4
	v_mul_lo_u32 v1, v3, v4
	v_mul_hi_u32 v1, v4, v1
	v_add_u32_e32 v1, v4, v1
	v_mul_hi_u32 v1, v5, v1
	v_mul_lo_u32 v3, v1, v2
	v_sub_u32_e32 v3, v5, v3
	v_add_u32_e32 v4, 1, v1
	v_cmp_ge_u32_e32 vcc, v3, v2
	s_nop 1
	v_cndmask_b32_e32 v1, v1, v4, vcc
	v_sub_u32_e32 v4, v3, v2
	v_cndmask_b32_e32 v3, v3, v4, vcc
	v_add_u32_e32 v4, 1, v1
	v_cmp_ge_u32_e32 vcc, v3, v2
	v_add_u32_e32 v3, 1, v5
	s_nop 0
	v_cndmask_b32_e32 v1, v1, v4, vcc
	v_mul_lo_u32 v4, v2, v1
	v_add_u32_e32 v2, v4, v2
	v_cmp_ne_u32_e32 vcc, v3, v2
	s_and_saveexec_b64 s[6:7], vcc
	s_xor_b64 s[6:7], exec, s[6:7]
	s_cbranch_execz .LBB0_974
	v_readlane_b32 s8, v252, 3
	v_readlane_b32 s9, v252, 4
	s_waitcnt lgkmcnt(0)
	s_nop 3
	global_load_dword v0, v197, s[8:9] sc1
	s_waitcnt vmcnt(0)
	v_cmp_eq_u32_e32 vcc, v0, v1
	s_and_saveexec_b64 s[8:9], vcc
	s_cbranch_execz .LBB0_973
	s_mov_b32 s3, 1
	s_mov_b64 s[12:13], 0
	s_branch .LBB0_964

; __device__ __forceinline__ unsigned xb_ld(unsigned* p)              { return __hip_atomic_load(p, __ATOMIC_RELAXED, __HIP_MEMORY_SCOPE_AGENT); }
; __device__ __forceinline__ unsigned xb_add(unsigned* p, unsigned v) { return __hip_atomic_fetch_add(p, v, __ATOMIC_RELAXED, __HIP_MEMORY_SCOPE_AGENT); }
; #define XB_SPIN(cond, bar) do { unsigned _sp = 0; while (cond) { __builtin_amdgcn_s_sleep(1); \
;     if ((++_sp & 255u) == 0u) { if (xb_ld(&(bar)[XB_TMO])) break; if (_sp > XB_SPIN_CAP) { atomicAdd(&(bar)[XB_TMO], 1u); break; } } } } while (0)
; __device__ __forceinline__ void xcd_barrier(const XcdBarrier& b) {
;     ...
;         const unsigned old = xb_add(&bar[XB_XSUB(b.x)], 1u);
;         const unsigned gen = old / nloc;
;         if (old + 1u == (gen + 1u) * nloc) {
;             __builtin_amdgcn_fence(__ATOMIC_RELEASE, "agent");
;             asm volatile("s_waitcnt vmcnt(0)" ::: "memory");
;             const unsigned og = xb_add(&bar[XB_TOP], 1u);
;             const unsigned tg = og / nx;
;             if (og + 1u == (tg + 1u) * nx) xb_add(&bar[XB_TOPGEN], 1u);
;             else XB_SPIN(xb_ld(&bar[XB_TOPGEN]) == tg, bar);
;             __builtin_amdgcn_fence(__ATOMIC_ACQUIRE, "agent");
;             xb_add(&bar[XB_XGEN(b.x)], 1u);
;             asm volatile("s_waitcnt vmcnt(0)" ::: "memory");
;         } else {
;             XB_SPIN(xb_ld(&bar[XB_XGEN(b.x)]) == gen, bar);
;             __builtin_amdgcn_fence(__ATOMIC_ACQUIRE, "agent");
;             asm volatile("s_waitcnt vmcnt(0)" ::: "memory");
.LBB0_973:
	s_or_b64 exec, exec, s[8:9]
	s_waitcnt vmcnt(0)
	buffer_inv sc1
	s_waitcnt vmcnt(0)
.LBB0_974:
	s_andn2_saveexec_b64 s[6:7], s[6:7]
	s_cbranch_execz .LBB0_994
	s_mov_b64 s[8:9], exec
	buffer_wbl2 sc1
	s_waitcnt lgkmcnt(0)
	s_waitcnt vmcnt(0)
	v_mbcnt_lo_u32_b32 v1, s8, 0
	v_mbcnt_hi_u32_b32 v1, s9, v1
	v_cmp_eq_u32_e32 vcc, 0, v1
	s_and_saveexec_b64 s[12:13], vcc
	s_cbranch_execz .LBB0_977
	s_bcnt1_i32_b64 s3, s[8:9]
	v_readlane_b32 s8, v252, 5
	v_mov_b32_e32 v2, s3
	v_readlane_b32 s9, v252, 6
	s_nop 4
	global_atomic_add v2, v197, v2, s[8:9] sc0

; __device__ __forceinline__ unsigned xb_ld(unsigned* p)              { return __hip_atomic_load(p, __ATOMIC_RELAXED, __HIP_MEMORY_SCOPE_AGENT); }
; __device__ __forceinline__ unsigned xb_add(unsigned* p, unsigned v) { return __hip_atomic_fetch_add(p, v, __ATOMIC_RELAXED, __HIP_MEMORY_SCOPE_AGENT); }
; #define XB_SPIN(cond, bar) do { unsigned _sp = 0; while (cond) { __builtin_amdgcn_s_sleep(1); \
;     if ((++_sp & 255u) == 0u) { if (xb_ld(&(bar)[XB_TMO])) break; if (_sp > XB_SPIN_CAP) { atomicAdd(&(bar)[XB_TMO], 1u); break; } } } } while (0)
; __device__ __forceinline__ void xcd_barrier(const XcdBarrier& b) {
;     ...
;             if (og + 1u == (tg + 1u) * nx) xb_add(&bar[XB_TOPGEN], 1u);
;             else XB_SPIN(xb_ld(&bar[XB_TOPGEN]) == tg, bar);
;             __builtin_amdgcn_fence(__ATOMIC_ACQUIRE, "agent");
;             xb_add(&bar[XB_XGEN(b.x)], 1u);
;             asm volatile("s_waitcnt vmcnt(0)" ::: "memory");
.LBB0_991:
	s_or_b64 exec, exec, s[8:9]
	s_mov_b64 s[8:9], exec
	v_mbcnt_lo_u32_b32 v0, s8, 0
	v_mbcnt_hi_u32_b32 v0, s9, v0
	v_cmp_eq_u32_e32 vcc, 0, v0
	s_waitcnt vmcnt(0)
	buffer_inv sc1
	s_and_saveexec_b64 s[12:13], vcc
	s_cbranch_execz .LBB0_993
	s_bcnt1_i32_b64 s3, s[8:9]
	v_readlane_b32 s8, v252, 3
	v_mov_b32_e32 v0, s3
	v_readlane_b32 s9, v252, 4
	s_nop 4
	global_atomic_add v197, v0, s[8:9]

; __device__ __forceinline__ unsigned xb_ld(unsigned* p)              { return __hip_atomic_load(p, __ATOMIC_RELAXED, __HIP_MEMORY_SCOPE_AGENT); }
; __device__ __forceinline__ unsigned xb_add(unsigned* p, unsigned v) { return __hip_atomic_fetch_add(p, v, __ATOMIC_RELAXED, __HIP_MEMORY_SCOPE_AGENT); }
; #define XB_SPIN(cond, bar) do { unsigned _sp = 0; while (cond) { __builtin_amdgcn_s_sleep(1); \
;     if ((++_sp & 255u) == 0u) { if (xb_ld(&(bar)[XB_TMO])) break; if (_sp > XB_SPIN_CAP) { atomicAdd(&(bar)[XB_TMO], 1u); break; } } } } while (0)
; __device__ __forceinline__ void xcd_barrier(const XcdBarrier& b) {
;     ...
;         __builtin_amdgcn_s_waitcnt(0);
;         unsigned nloc = b.st[0], nx = b.st[1];
;         if (nloc == 0u) { xcd_barrier_complete(bar, b.x, nloc, nx); b.st[0] = nloc; b.st[1] = nx; }
;         const unsigned old = xb_add(&bar[XB_XSUB(b.x)], 1u);
;         const unsigned gen = old / nloc;
;         if (old + 1u == (gen + 1u) * nloc) {
;             __builtin_amdgcn_fence(__ATOMIC_RELEASE, "agent");
;             asm volatile("s_waitcnt vmcnt(0)" ::: "memory");
;             const unsigned og = xb_add(&bar[XB_TOP], 1u);
;             const unsigned tg = og / nx;
;             if (og + 1u == (tg + 1u) * nx) xb_add(&bar[XB_TOPGEN], 1u);
;             else XB_SPIN(xb_ld(&bar[XB_TOPGEN]) == tg, bar);
;             __builtin_amdgcn_fence(__ATOMIC_ACQUIRE, "agent");
;             xb_add(&bar[XB_XGEN(b.x)], 1u);
;             asm volatile("s_waitcnt vmcnt(0)" ::: "memory");
;         } else {
;             XB_SPIN(xb_ld(&bar[XB_XGEN(b.x)]) == gen, bar);
.LBB0_1037:
	s_or_b64 exec, exec, s[4:5]
	v_cvt_f32_u32_e32 v4, v2
	s_waitcnt vmcnt(0)
	v_readfirstlane_b32 s3, v3
	v_sub_u32_e32 v3, 0, v2
	v_rcp_iflag_f32_e32 v4, v4
	v_add_u32_e32 v5, s3, v1
	v_mul_f32_e32 v4, 0x4f7ffffe, v4
	v_cvt_u32_f32_e32 v4, v4
	v_mul_lo_u32 v1, v3, v4
	v_mul_hi_u32 v1, v4, v1
	v_add_u32_e32 v1, v4, v1
	v_mul_hi_u32 v1, v5, v1
	v_mul_lo_u32 v3, v1, v2
	v_sub_u32_e32 v3, v5, v3
	v_add_u32_e32 v4, 1, v1
	v_cmp_ge_u32_e32 vcc, v3, v2
	s_nop 1
	v_cndmask_b32_e32 v1, v1, v4, vcc
	v_sub_u32_e32 v4, v3, v2
	v_cndmask_b32_e32 v3, v3, v4, vcc
	v_add_u32_e32 v4, 1, v1
	v_cmp_ge_u32_e32 vcc, v3, v2
	v_add_u32_e32 v3, 1, v5
	s_nop 0
	v_cndmask_b32_e32 v1, v1, v4, vcc
	v_mul_lo_u32 v4, v2, v1
	v_add_u32_e32 v2, v4, v2
	v_cmp_ne_u32_e32 vcc, v3, v2
	s_and_saveexec_b64 s[4:5], vcc
	s_xor_b64 s[4:5], exec, s[4:5]
	s_cbranch_execz .LBB0_1051
	v_readlane_b32 s6, v252, 3
	v_readlane_b32 s7, v252, 4
	s_waitcnt lgkmcnt(0)
	s_nop 3
	global_load_dword v0, v197, s[6:7] sc1
	s_waitcnt vmcnt(0)
	v_cmp_eq_u32_e32 vcc, v0, v1
	s_and_saveexec_b64 s[6:7], vcc
	s_cbranch_execz .LBB0_1050
	s_mov_b32 s3, 1
	s_mov_b64 s[8:9], 0
	s_branch .LBB0_1041

; __device__ __forceinline__ unsigned xb_ld(unsigned* p)              { return __hip_atomic_load(p, __ATOMIC_RELAXED, __HIP_MEMORY_SCOPE_AGENT); }
; #define XB_SPIN(cond, bar) do { unsigned _sp = 0; while (cond) { __builtin_amdgcn_s_sleep(1); \
;     if ((++_sp & 255u) == 0u) { if (xb_ld(&(bar)[XB_TMO])) break; if (_sp > XB_SPIN_CAP) { atomicAdd(&(bar)[XB_TMO], 1u); break; } } } } while (0)
; __device__ __forceinline__ void xcd_barrier(const XcdBarrier& b) {
;     ...
;             XB_SPIN(xb_ld(&bar[XB_XGEN(b.x)]) == gen, bar);
;             __builtin_amdgcn_fence(__ATOMIC_ACQUIRE, "agent");
;             asm volatile("s_waitcnt vmcnt(0)" ::: "memory");
.LBB0_1050:
	s_or_b64 exec, exec, s[6:7]
	s_waitcnt vmcnt(0)
	buffer_inv sc1
	s_waitcnt vmcnt(0)

; __device__ __forceinline__ unsigned xb_add(unsigned* p, unsigned v) { return __hip_atomic_fetch_add(p, v, __ATOMIC_RELAXED, __HIP_MEMORY_SCOPE_AGENT); }
; __device__ __forceinline__ void xcd_barrier(const XcdBarrier& b) {
;     ...
;         if (old + 1u == (gen + 1u) * nloc) {
;             __builtin_amdgcn_fence(__ATOMIC_RELEASE, "agent");
;             asm volatile("s_waitcnt vmcnt(0)" ::: "memory");
;             const unsigned og = xb_add(&bar[XB_TOP], 1u);
.LBB0_1052:
	s_mov_b64 s[6:7], exec
	buffer_wbl2 sc1
	s_waitcnt lgkmcnt(0)
	s_waitcnt vmcnt(0)
	v_mbcnt_lo_u32_b32 v1, s6, 0
	v_mbcnt_hi_u32_b32 v1, s7, v1
	v_cmp_eq_u32_e32 vcc, 0, v1
	s_and_saveexec_b64 s[8:9], vcc
	s_cbranch_execz .LBB0_1054
	s_bcnt1_i32_b64 s3, s[6:7]
	v_readlane_b32 s6, v252, 5
	v_mov_b32_e32 v2, s3
	v_readlane_b32 s7, v252, 6
	s_nop 4
	global_atomic_add v2, v197, v2, s[6:7] sc0

; __device__ __forceinline__ unsigned xb_ld(unsigned* p)              { return __hip_atomic_load(p, __ATOMIC_RELAXED, __HIP_MEMORY_SCOPE_AGENT); }
; __device__ __forceinline__ unsigned xb_add(unsigned* p, unsigned v) { return __hip_atomic_fetch_add(p, v, __ATOMIC_RELAXED, __HIP_MEMORY_SCOPE_AGENT); }
; #define XB_SPIN(cond, bar) do { unsigned _sp = 0; while (cond) { __builtin_amdgcn_s_sleep(1); \
;     if ((++_sp & 255u) == 0u) { if (xb_ld(&(bar)[XB_TMO])) break; if (_sp > XB_SPIN_CAP) { atomicAdd(&(bar)[XB_TMO], 1u); break; } } } } while (0)
; __device__ __forceinline__ void xcd_barrier(const XcdBarrier& b) {
;     ...
;             if (og + 1u == (tg + 1u) * nx) xb_add(&bar[XB_TOPGEN], 1u);
;             else XB_SPIN(xb_ld(&bar[XB_TOPGEN]) == tg, bar);
;             __builtin_amdgcn_fence(__ATOMIC_ACQUIRE, "agent");
;             xb_add(&bar[XB_XGEN(b.x)], 1u);
;             asm volatile("s_waitcnt vmcnt(0)" ::: "memory");
.LBB0_1068:
	s_or_b64 exec, exec, s[6:7]
	s_mov_b64 s[6:7], exec
	v_mbcnt_lo_u32_b32 v0, s6, 0
	v_mbcnt_hi_u32_b32 v0, s7, v0
	v_cmp_eq_u32_e32 vcc, 0, v0
	s_waitcnt vmcnt(0)
	buffer_inv sc1
	s_and_saveexec_b64 s[8:9], vcc
	s_cbranch_execnz .LBB0_1069
	s_getpc_b64 s[98:99]
